# MLA attention unit body hand-scheduled too: rolling LDS fragment window with counted waits, softmax VALU interleaved with MFMAs, half of exp deferred into next tile QK gaps
# speedup vs baseline: 1.0130x; 1.0130x over previous
; #define LAS __attribute__((address_space(3)))
; #define MFMA32(a, b, c) __builtin_amdgcn_mfma_f32_32x32x16_bf16((a), (b), (c), 0, 0, 0)
; __device__ __forceinline__ void att1_load(bf16x8 (&kf)[8], bf16x8 (&vf)[8], const LAS unsigned char* kslot, int ka, const LAS unsigned char* vslot, int va) {
; #pragma unroll
;     for (int ks = 0; ks < 4; ++ks) { const LAS unsigned char* p = kslot + (ka ^ (ks * 32)); kf[2 * ks] = *(const LAS bf16x8*)p; kf[2 * ks + 1] = *(const LAS bf16x8*)(p + 32 * 256); }
; #pragma unroll
;     for (int kk = 0; kk < 2; ++kk)
; #pragma unroll
;         for (int db = 0; db < 4; ++db) vf[kk * 4 + db] = *(const LAS bf16x8*)(vslot + ((va ^ (kk * 32)) + db * 4096));
; }
; __device__ __forceinline__ void att1_load2(bf16x8 (&vg)[8], const LAS unsigned char* vslot, int va) {
; #pragma unroll
;     for (int kk = 2; kk < 4; ++kk)
; #pragma unroll
;         for (int db = 0; db < 4; ++db) vg[(kk - 2) * 4 + db] = *(const LAS bf16x8*)(vslot + ((va ^ (kk * 32)) + db * 4096));
; }
; __device__ __forceinline__ void att1_qk(f32x16& s0, f32x16& s1, const bf16x8 (&kf)[8], const bf16x8 (&qf)[4]) {
;     f32x16 z;
; #pragma unroll
;     for (int i = 0; i < 16; ++i) z[i] = 0.f;
;     s0 = MFMA32(kf[0], qf[0], z); s1 = MFMA32(kf[1], qf[0], z);
; #pragma unroll
;     for (int ks = 1; ks < 4; ++ks) { s0 = MFMA32(kf[2 * ks], qf[ks], s0); s1 = MFMA32(kf[2 * ks + 1], qf[ks], s1); }
; }
; __device__ __forceinline__ void att1_pv(f32x16 (&o)[4], const bf16x8 (&vf)[8], const bf16x8 (&vg)[8], const bf16x8 (&pf)[4]) {
; #pragma unroll
;     for (int kk = 0; kk < 2; ++kk)
; #pragma unroll
;         for (int db = 0; db < 4; ++db) o[db] = MFMA32(vf[kk * 4 + db], pf[kk], o[db]);
; #pragma unroll
;     for (int kk = 2; kk < 4; ++kk)
; #pragma unroll
;         for (int db = 0; db < 4; ++db) o[db] = MFMA32(vg[(kk - 2) * 4 + db], pf[kk], o[db]);
; }
.Lda_loop:
	v_add_u32_e32 v216, s67, v132
	v_add_u32_e32 v217, s67, v137
	v_add_u32_e32 v218, s67, v138
	v_add_u32_e32 v219, s67, v139
	ds_read_b128 v[140:143], v216
	ds_read_b128 v[144:147], v217
	ds_read_b128 v[148:151], v218
	ds_read_b128 v[152:155], v219
	ds_read_b128 v[156:159], v216 offset:8192
	ds_read_b128 v[160:163], v217 offset:8192
	ds_read_b128 v[164:167], v218 offset:8192
	ds_read_b128 v[168:171], v219 offset:8192
	v_add_u32_e32 v220, s38, v176
	v_add_u32_e32 v221, s38, v177
	v_add_u32_e32 v222, s38, v178
	v_add_u32_e32 v223, s38, v179
	ds_read_b128 v[184:187], v220 offset:49152
	ds_read_b128 v[188:191], v220 offset:53248
	ds_read_b128 v[192:195], v220 offset:57344
	ds_read_b128 v[196:199], v220 offset:61440
	ds_read_b128 v[200:203], v221 offset:49152
	ds_read_b128 v[204:207], v221 offset:53248
	ds_read_b128 v[208:211], v221 offset:57344
	v_exp_f32_e32 v80, v80
	v_exp_f32_e32 v81, v81
	v_add_f32_e32 v133, v133, v80
	v_add_f32_e32 v136, v136, v81
	v_exp_f32_e32 v82, v82
	v_exp_f32_e32 v83, v83
	v_add_f32_e32 v133, v133, v82
	v_add_f32_e32 v136, v136, v83
	s_waitcnt lgkmcnt(11)
	v_mfma_f32_32x32x16_bf16 v[64:79], v[140:143], v[108:111], v[236:251]
	ds_read_b128 v[212:215], v221 offset:61440
	v_exp_f32_e32 v84, v84
	v_exp_f32_e32 v85, v85
	v_add_f32_e32 v133, v133, v84
	v_add_f32_e32 v136, v136, v85
	v_mfma_f32_32x32x16_bf16 v[64:79], v[144:147], v[104:107], v[64:79]
	ds_read_b128 v[140:143], v222 offset:49152
	v_exp_f32_e32 v86, v86
	v_exp_f32_e32 v87, v87
	v_add_f32_e32 v133, v133, v86
	v_add_f32_e32 v136, v136, v87
	v_mfma_f32_32x32x16_bf16 v[64:79], v[148:151], v[100:103], v[64:79]
	ds_read_b128 v[144:147], v222 offset:53248
	v_exp_f32_e32 v88, v88
	v_exp_f32_e32 v89, v89
	v_add_f32_e32 v133, v133, v88
	v_add_f32_e32 v136, v136, v89
	v_cvt_pk_bf16_f32 v120, v80, v81
	v_cvt_pk_bf16_f32 v121, v82, v83
	v_mfma_f32_32x32x16_bf16 v[64:79], v[152:155], v[96:99], v[64:79]
	ds_read_b128 v[148:151], v222 offset:57344
	v_exp_f32_e32 v90, v90
	v_exp_f32_e32 v91, v91
	v_add_f32_e32 v133, v133, v90
	v_add_f32_e32 v136, v136, v91
	v_cvt_pk_bf16_f32 v122, v84, v85
	v_cvt_pk_bf16_f32 v123, v86, v87
	s_waitcnt lgkmcnt(7)
	v_mfma_f32_32x32x16_bf16 v[48:63], v[184:187], v[112:115], v[48:63]
	ds_read_b128 v[152:155], v222 offset:61440
	v_exp_f32_e32 v92, v92
	v_exp_f32_e32 v93, v93
	v_add_f32_e32 v133, v133, v92
	v_add_f32_e32 v136, v136, v93
	v_mfma_f32_32x32x16_bf16 v[32:47], v[188:191], v[112:115], v[32:47]
	v_exp_f32_e32 v94, v94
	v_exp_f32_e32 v95, v95
	v_add_f32_e32 v133, v133, v94
	v_add_f32_e32 v136, v136, v95
	v_mfma_f32_32x32x16_bf16 v[16:31], v[192:195], v[112:115], v[16:31]
	v_cvt_pk_bf16_f32 v124, v88, v89
	v_cvt_pk_bf16_f32 v125, v90, v91
	v_cvt_pk_bf16_f32 v126, v92, v93
	v_cvt_pk_bf16_f32 v127, v94, v95
	v_max3_f32 v224, v64, v65, v66
	v_max3_f32 v225, v67, v68, v69
	v_mfma_f32_32x32x16_bf16 v[0:15], v[196:199], v[112:115], v[0:15]
	v_max3_f32 v224, v224, v70, v71
	v_max3_f32 v225, v225, v72, v73
	v_max3_f32 v224, v224, v74, v75
	v_max3_f32 v225, v225, v76, v77
	v_max3_f32 v224, v224, v78, v79
	v_mfma_f32_32x32x16_bf16 v[80:95], v[156:159], v[108:111], v[236:251]
	s_add_i32 s3, s58, s38
	s_mov_b32 m0, s3
	s_nop 0
	global_load_lds_dwordx4 v128, s[8:9]
	v_mfma_f32_32x32x16_bf16 v[80:95], v[160:163], v[104:107], v[80:95]
	ds_read_b128 v[156:159], v223 offset:49152
	s_addk_i32 s3, 0x2000
	s_mov_b32 m0, s3
	s_nop 0
	global_load_lds_dwordx4 v129, s[8:9]
	v_mfma_f32_32x32x16_bf16 v[80:95], v[164:167], v[100:103], v[80:95]
	ds_read_b128 v[160:163], v223 offset:53248
	s_add_i32 s3, s65, s39
	s_mov_b32 m0, s3
	s_nop 0
	global_load_lds_dwordx4 v130, s[10:11]
	v_mfma_f32_32x32x16_bf16 v[80:95], v[168:171], v[96:99], v[80:95]
	ds_read_b128 v[164:167], v223 offset:57344
	s_addk_i32 s3, 0x2000
	s_mov_b32 m0, s3
	s_nop 0
	global_load_lds_dwordx4 v131, s[10:11]
	s_waitcnt lgkmcnt(7)
	v_mfma_f32_32x32x16_bf16 v[48:63], v[200:203], v[116:119], v[48:63]
	ds_read_b128 v[168:171], v223 offset:61440
	s_cmp_lt_u32 s66, 125
	s_cselect_b32 s36, 0x4000, 0
	s_add_u32 s8, s8, s36
	s_addc_u32 s9, s9, 0
	v_mfma_f32_32x32x16_bf16 v[32:47], v[204:207], v[116:119], v[32:47]
	s_cmp_lt_u32 s66, 126
	s_cselect_b32 s36, 0x80, 0
	s_add_u32 s10, s10, s36
	s_addc_u32 s11, s11, 0
	s_nop 3
	v_max3_f32 v224, v224, v80, v81
	v_max3_f32 v225, v225, v82, v83
	v_max3_f32 v224, v224, v84, v85
	v_max3_f32 v225, v225, v86, v87
	v_mfma_f32_32x32x16_bf16 v[16:31], v[208:211], v[116:119], v[16:31]
	v_max3_f32 v224, v224, v88, v89
	v_max3_f32 v225, v225, v90, v91
	v_max3_f32 v224, v224, v92, v93
	v_max3_f32 v225, v225, v94, v95
	v_max_f32_e32 v224, v224, v225
	v_mov_b32_e32 v225, v224
	s_nop 1
	v_permlane32_swap_b32_e32 v224, v225
	v_max_f32_e32 v224, v224, v225
	v_cmp_lt_f32_e32 vcc, 0x41000000, v224
	v_mfma_f32_32x32x16_bf16 v[0:15], v[212:215], v[116:119], v[0:15]
	s_nop 1
	s_cmp_lg_u64 vcc, 0
	s_cbranch_scc1 .Lda_rareA

; __device__ __forceinline__ unsigned pk2(float lo, float hi) { f32x2_t v = {lo, hi}; bf16x2_t b = __builtin_convertvector(v, bf16x2_t); return __builtin_bit_cast(unsigned, b); }
; __device__ __forceinline__ float xor32_add(float v) { auto rr = __builtin_amdgcn_permlane32_swap(__float_as_uint(v), __float_as_uint(v), false, false); return __uint_as_float(rr[0]) + __uint_as_float(rr[1]); }
; template <int MODE>
; __device__ __forceinline__ void attn_phase(LAS unsigned char* lds, const bf16* Qp, const bf16* Kp, const bf16* KPEp, const bf16* Vtp, bf16* CAT, float lam, int vcu, int G) {
;     ...
;         att_pv(o, vring + vr, va, pf);
;         asm volatile("s_waitcnt vmcnt(0) lgkmcnt(0)\n\ts_barrier" ::: "memory");
;     ...
;         lrun = xor32_add(lrun);
;         const float inv = 1.0f / lrun;
;         bf16* orow = CAT + qrow * DM + h * 128;
;         if (MODE == 0) {
; #pragma unroll
;             for (int db = 0; db < 4; ++db)
; #pragma unroll
;                 for (int g4 = 0; g4 < 4; ++g4) {
;                     const u32x2 w = {pk2(o[db][4 * g4] * inv, o[db][4 * g4 + 1] * inv), pk2(o[db][4 * g4 + 2] * inv, o[db][4 * g4 + 3] * inv)};
;                     *(u32x2*)(orow + 32 * db + 8 * g4 + 4 * hh) = w;
;                 }
.Lma_epi:
	v_mov_b32_e32 v64, v185
	s_nop 1
	v_permlane32_swap_b32_e32 v185, v64
	v_add_f32_e32 v64, v185, v64
	v_div_scale_f32 v65, s[4:5], v64, v64, 1.0
	v_rcp_f32_e32 v66, v65
	s_nop 0
	v_fma_f32 v67, -v65, v66, 1.0
	v_fmac_f32_e32 v66, v67, v66
	v_div_scale_f32 v67, vcc, 1.0, v64, 1.0
	v_mul_f32_e32 v68, v67, v66
	v_fma_f32 v69, -v65, v68, v67
	v_fmac_f32_e32 v68, v69, v66
	v_fma_f32 v65, -v65, v68, v67
	v_div_fmas_f32 v65, v65, v66, v68
	v_lshlrev_b64 v[66:67], 11, v[160:161]
	v_div_fixup_f32 v64, v65, v64, 1.0
	v_lshl_add_u64 v[66:67], s[10:11], 0, v[66:67]
	v_lshl_add_u64 v[66:67], v[66:67], 0, s[36:37]
	v_pk_mul_f32 v[48:49], v[48:49], v[64:65] op_sel_hi:[1,0]
	v_pk_mul_f32 v[50:51], v[50:51], v[64:65] op_sel_hi:[1,0]
	v_pk_mul_f32 v[32:33], v[32:33], v[64:65] op_sel_hi:[1,0]
	v_pk_mul_f32 v[34:35], v[34:35], v[64:65] op_sel_hi:[1,0]
	v_pk_mul_f32 v[16:17], v[16:17], v[64:65] op_sel_hi:[1,0]
	v_pk_mul_f32 v[18:19], v[18:19], v[64:65] op_sel_hi:[1,0]
	v_pk_mul_f32 v[0:1], v[0:1], v[64:65] op_sel_hi:[1,0]
	v_pk_mul_f32 v[2:3], v[2:3], v[64:65] op_sel_hi:[1,0]
	v_lshl_add_u64 v[66:67], v[66:67], 0, v[232:233]
	v_cvt_pk_bf16_f32 v48, v48, v49
	v_cvt_pk_bf16_f32 v49, v50, v51
	v_cvt_pk_bf16_f32 v32, v32, v33
	v_cvt_pk_bf16_f32 v33, v34, v35
	v_cvt_pk_bf16_f32 v16, v16, v17
	v_cvt_pk_bf16_f32 v17, v18, v19
	v_cvt_pk_bf16_f32 v0, v0, v1
	v_cvt_pk_bf16_f32 v1, v2, v3
	global_store_dwordx2 v[66:67], v[48:49], off
	v_pk_mul_f32 v[48:49], v[52:53], v[64:65] op_sel_hi:[1,0]
	v_pk_mul_f32 v[50:51], v[54:55], v[64:65] op_sel_hi:[1,0]
	global_store_dwordx2 v[66:67], v[32:33], off offset:64
	v_pk_mul_f32 v[32:33], v[36:37], v[64:65] op_sel_hi:[1,0]
	v_pk_mul_f32 v[34:35], v[38:39], v[64:65] op_sel_hi:[1,0]
	global_store_dwordx2 v[66:67], v[16:17], off offset:128
	v_pk_mul_f32 v[16:17], v[20:21], v[64:65] op_sel_hi:[1,0]
	v_pk_mul_f32 v[18:19], v[22:23], v[64:65] op_sel_hi:[1,0]
	global_store_dwordx2 v[66:67], v[0:1], off offset:192
	v_pk_mul_f32 v[0:1], v[4:5], v[64:65] op_sel_hi:[1,0]
	v_pk_mul_f32 v[2:3], v[6:7], v[64:65] op_sel_hi:[1,0]
	v_cvt_pk_bf16_f32 v48, v48, v49
	v_cvt_pk_bf16_f32 v49, v50, v51
	v_cvt_pk_bf16_f32 v32, v32, v33
	v_cvt_pk_bf16_f32 v33, v34, v35
	v_cvt_pk_bf16_f32 v16, v16, v17
	v_cvt_pk_bf16_f32 v17, v18, v19
	v_cvt_pk_bf16_f32 v0, v0, v1
	v_cvt_pk_bf16_f32 v1, v2, v3
	global_store_dwordx2 v[66:67], v[48:49], off offset:16
	v_pk_mul_f32 v[48:49], v[56:57], v[64:65] op_sel_hi:[1,0]
	v_pk_mul_f32 v[50:51], v[58:59], v[64:65] op_sel_hi:[1,0]
	global_store_dwordx2 v[66:67], v[32:33], off offset:80
	v_pk_mul_f32 v[32:33], v[40:41], v[64:65] op_sel_hi:[1,0]
	v_pk_mul_f32 v[34:35], v[42:43], v[64:65] op_sel_hi:[1,0]
	global_store_dwordx2 v[66:67], v[16:17], off offset:144
	v_pk_mul_f32 v[16:17], v[24:25], v[64:65] op_sel_hi:[1,0]
	v_pk_mul_f32 v[18:19], v[26:27], v[64:65] op_sel_hi:[1,0]
	global_store_dwordx2 v[66:67], v[0:1], off offset:208
	v_pk_mul_f32 v[0:1], v[8:9], v[64:65] op_sel_hi:[1,0]
	v_pk_mul_f32 v[2:3], v[10:11], v[64:65] op_sel_hi:[1,0]
	v_cvt_pk_bf16_f32 v48, v48, v49
	v_cvt_pk_bf16_f32 v49, v50, v51
	v_cvt_pk_bf16_f32 v32, v32, v33
	v_cvt_pk_bf16_f32 v33, v34, v35
	v_cvt_pk_bf16_f32 v16, v16, v17
	v_cvt_pk_bf16_f32 v17, v18, v19
	v_cvt_pk_bf16_f32 v0, v0, v1
	v_cvt_pk_bf16_f32 v1, v2, v3
	global_store_dwordx2 v[66:67], v[48:49], off offset:32
	v_pk_mul_f32 v[48:49], v[60:61], v[64:65] op_sel_hi:[1,0]
	v_pk_mul_f32 v[50:51], v[62:63], v[64:65] op_sel_hi:[1,0]
	global_store_dwordx2 v[66:67], v[32:33], off offset:96
	v_pk_mul_f32 v[32:33], v[44:45], v[64:65] op_sel_hi:[1,0]
	v_pk_mul_f32 v[34:35], v[46:47], v[64:65] op_sel_hi:[1,0]
	global_store_dwordx2 v[66:67], v[16:17], off offset:160
	v_pk_mul_f32 v[16:17], v[28:29], v[64:65] op_sel_hi:[1,0]
	v_pk_mul_f32 v[18:19], v[30:31], v[64:65] op_sel_hi:[1,0]
	global_store_dwordx2 v[66:67], v[0:1], off offset:224
	v_pk_mul_f32 v[0:1], v[12:13], v[64:65] op_sel_hi:[1,0]
	v_pk_mul_f32 v[2:3], v[14:15], v[64:65] op_sel_hi:[1,0]
	v_cvt_pk_bf16_f32 v48, v48, v49
	v_cvt_pk_bf16_f32 v49, v50, v51
	v_cvt_pk_bf16_f32 v32, v32, v33
	v_cvt_pk_bf16_f32 v33, v34, v35
	v_cvt_pk_bf16_f32 v16, v16, v17
	v_cvt_pk_bf16_f32 v17, v18, v19
	v_cvt_pk_bf16_f32 v0, v0, v1
	v_cvt_pk_bf16_f32 v1, v2, v3
	global_store_dwordx2 v[66:67], v[48:49], off offset:48
	global_store_dwordx2 v[66:67], v[32:33], off offset:112
	global_store_dwordx2 v[66:67], v[16:17], off offset:176
	global_store_dwordx2 v[66:67], v[0:1], off offset:240
	s_cbranch_scc1 .LBB0_1356
; template <int MODE>
; __device__ __forceinline__ void attn_phase(LAS unsigned char* lds, const bf16* Qp, const bf16* Kp, const bf16* KPEp, const bf16* Vtp, bf16* CAT, float lam, int vcu, int G) {
;     ...
;         int tid_ = threadIdx.x; asm volatile("" : "+v"(tid_)); const int tid = tid_, lane = tid & 63, wave = __builtin_amdgcn_readfirstlane(tid >> 6), r = lane & 31, hh = lane >> 5;
;         int b, h, q0, wq, map, bh;
;         if (MODE == 0) { const int qb = unit & 31; bh = unit >> 5; b = bh >> 2; h = bh & 3; q0 = qb * 256; wq = wave; map = 0; }
;         else { const int qb = unit & 63; bh = unit >> 6; b = bh >> 3; h = bh & 7; q0 = qb * 128; wq = wave & 3; map = wave >> 2; }
;         const size_t rowbase = (size_t)b * SEQ;
;         const size_t qrow = rowbase + q0 + 32 * wq + r;
;         bf16x8 qf[NKS];
;         {
;             const bf16* qp = MODE == 0 ? Qp + qrow * 768 + h * 192 + 8 * hh : Qp + qrow * 1024 + (2 * h + map) * 64 + 8 * hh;
; #pragma unroll
;             for (int ks = 0; ks < NKS; ++ks) qf[ks] = *(const bf16x8*)(qp + 16 * ks);
;         }
;         const bf16* kp[NKI]; int kadv[NKI];
; #pragma unroll
;         for (int n = 0; n < NKI; ++n) {
;             const int P = 64 * (wave + 8 * n) + lane;
;             if (MODE == 0) {
;                 const int row = P / 24, cp = P - row * 24, c = (cp & ~7) | ((cp & 7) ^ ((row >> 1) & 7));
;                 if (c < 16) { kp[n] = Kp + (rowbase + row) * 512 + h * 128 + c * 8; kadv[n] = 64 * 512; }
;                 else { kp[n] = KPEp + (rowbase + row) * 64 + (c - 16) * 8; kadv[n] = 64 * 64; }
;             } else {
;                 const int row = P >> 4, c = (P & 15) ^ (row & 15);
;                 kp[n] = Kp + (rowbase + row) * 1024 + h * 128 + c * 8; kadv[n] = 64 * 1024;
;             }
;         }
;         const bf16* vp[2];
; #pragma unroll
;         for (int n = 0; n < 2; ++n) { const int P = 64 * (wave + 8 * n) + lane, dv = P >> 3, c = (P & 7) ^ ((dv >> 1) & 7); vp[n] = Vtp + ((size_t)(bh * 128 + dv)) * SEQ + c * 8; }
;         const unsigned kdma = lds0 + wave * 1024, vdma = lds0 + 3 * KB + wave * 1024;
;     ...
;         const int ka = MODE == 0 ? r * RB + ((hh ^ ((r >> 1) & 7)) * 16) : r * RB + (((map * 8 + hh) ^ (r & 15)) * 16);
;         const int va = r * 128 + ((hh ^ ((r >> 1) & 7)) * 16);
;         const LAS unsigned char* vring = lds + 3 * KB;
;         f32x16 o[4], S0, S1;
.LBB0_1339:
	v_mov_b32_e32 v14, v235
	s_ashr_i32 s4, s17, 7
	v_readfirstlane_b32 s38, v14
	s_lshl_b32 s5, s17, 8
	s_ashr_i32 s40, s38, 6
	v_and_b32_e32 v3, 31, v14
	s_and_b32 s36, s5, 0x1f00
	s_ashr_i32 s5, s4, 31
	s_lshl_b64 s[6:7], s[4:5], 13
	s_lshl_b32 s4, s40, 5
	v_or_b32_e32 v0, s36, v3
	s_ashr_i32 s5, s4, 31
	v_or_b32_e32 v0, s6, v0
	v_mov_b32_e32 v1, s7
	s_ashr_i32 s41, s17, 5
	v_lshl_add_u64 v[160:161], v[0:1], 0, s[4:5]
	v_mov_b64_e32 v[0:1], s[12:13]
	s_and_b32 s42, s41, 3
	v_mad_u64_u32 v[0:1], s[4:5], v160, s61, v[0:1]
	v_bfe_u32 v179, v14, 5, 1
	v_mad_i32_i24 v1, v161, s61, v1
	s_mul_i32 s36, s42, 0x180
	v_lshl_add_u64 v[0:1], v[0:1], 0, s[36:37]
	v_lshlrev_b32_e32 v232, 4, v179
	v_lshl_add_u64 v[0:1], v[0:1], 0, v[232:233]
	global_load_dwordx4 v[96:99], v[0:1], off
	global_load_dwordx4 v[100:103], v[0:1], off offset:32
	global_load_dwordx4 v[104:107], v[0:1], off offset:64
	global_load_dwordx4 v[108:111], v[0:1], off offset:96
	global_load_dwordx4 v[112:115], v[0:1], off offset:128
	global_load_dwordx4 v[116:119], v[0:1], off offset:160
	global_load_dwordx4 v[120:123], v[0:1], off offset:192
	global_load_dwordx4 v[124:127], v[0:1], off offset:224
	global_load_dwordx4 v[128:131], v[0:1], off offset:256
	global_load_dwordx4 v[132:135], v[0:1], off offset:288
	global_load_dwordx4 v[136:139], v[0:1], off offset:320
	global_load_dwordx4 v[140:143], v[0:1], off offset:352
	v_mov_b32_e32 v0, s38
	s_movk_i32 s3, 0xffc0
	v_bfi_b32 v2, s3, v0, v14
	v_mul_hi_i32 v0, v2, s96
	v_lshrrev_b32_e32 v1, 31, v0
	v_ashrrev_i32_e32 v0, 2, v0
	v_add_u32_e32 v0, v0, v1
	s_lshl_b32 s4, s42, 8
	v_lshrrev_b32_e32 v1, 1, v0
	s_add_u32 s38, s18, s4
	v_mad_u64_u32 v[4:5], s[4:5], v0, s66, v[2:3]
	v_xor_b32_e32 v1, v1, v14
	v_bfi_b32 v4, -8, v4, v1
	v_ashrrev_i32_e32 v1, 31, v0
	s_addc_u32 s39, s19, 0
	v_cmp_lt_i32_e32 vcc, 15, v4
	v_lshl_add_u64 v[6:7], s[6:7], 0, v[0:1]
	v_lshlrev_b32_e32 v4, 3, v4
	s_and_saveexec_b64 s[4:5], vcc
	s_xor_b64 s[4:5], exec, s[4:5]
	v_lshlrev_b64 v[0:1], 7, v[6:7]
	v_lshl_add_u64 v[0:1], s[28:29], 0, v[0:1]
	v_add_u32_e32 v232, 0xffffff80, v4
	v_lshl_add_u64 v[0:1], v[232:233], 1, v[0:1]
	s_or_saveexec_b64 s[4:5], s[4:5]
	v_mov_b64_e32 v[162:163], 0x1000
	s_xor_b64 exec, exec, s[4:5]
	v_lshlrev_b64 v[0:1], 10, v[6:7]
	v_lshl_add_u64 v[0:1], s[38:39], 0, v[0:1]
	v_ashrrev_i32_e32 v5, 31, v4
	v_lshl_add_u64 v[0:1], v[4:5], 1, v[0:1]
	v_mov_b64_e32 v[162:163], 0x8000
	s_or_b64 exec, exec, s[4:5]
	v_add_u32_e32 v6, 0x200, v2
	v_mul_hi_i32 v4, v6, s96
	v_lshrrev_b32_e32 v5, 31, v4
	v_ashrrev_i32_e32 v4, 2, v4
	v_add_u32_e32 v4, v4, v5
	v_lshrrev_b32_e32 v5, 1, v4
	v_mad_u64_u32 v[8:9], s[4:5], v4, s66, v[6:7]
	v_xor_b32_e32 v5, v5, v14
	v_bfi_b32 v7, -8, v8, v5
	v_ashrrev_i32_e32 v5, 31, v4
	v_cmp_lt_i32_e32 vcc, 15, v7
	v_lshl_add_u64 v[10:11], s[6:7], 0, v[4:5]
	v_lshlrev_b32_e32 v8, 3, v7
	s_and_saveexec_b64 s[4:5], vcc
	s_xor_b64 s[4:5], exec, s[4:5]
	v_lshlrev_b64 v[4:5], 7, v[10:11]
	v_lshl_add_u64 v[4:5], s[28:29], 0, v[4:5]
	v_add_u32_e32 v232, 0xffffff80, v8
	v_lshl_add_u64 v[4:5], v[232:233], 1, v[4:5]
	s_or_saveexec_b64 s[4:5], s[4:5]
	v_mov_b64_e32 v[164:165], 0x1000
	s_xor_b64 exec, exec, s[4:5]
	v_lshlrev_b64 v[4:5], 10, v[10:11]
	v_lshl_add_u64 v[4:5], s[38:39], 0, v[4:5]
	v_ashrrev_i32_e32 v9, 31, v8
	v_lshl_add_u64 v[4:5], v[8:9], 1, v[4:5]
	v_mov_b64_e32 v[164:165], 0x8000
	s_or_b64 exec, exec, s[4:5]
	v_add_u32_e32 v8, 0x400, v2
	v_mul_hi_i32 v7, v8, s96
	v_lshrrev_b32_e32 v9, 31, v7
	v_ashrrev_i32_e32 v7, 2, v7
	v_add_u32_e32 v10, v7, v9
	v_lshrrev_b32_e32 v7, 1, v10
	v_mad_u64_u32 v[8:9], s[4:5], v10, s66, v[8:9]
	v_xor_b32_e32 v7, v7, v14
	v_bfi_b32 v7, -8, v8, v7
	v_ashrrev_i32_e32 v11, 31, v10
	v_cmp_lt_i32_e32 vcc, 15, v7
	v_lshl_add_u64 v[12:13], s[6:7], 0, v[10:11]
	v_lshlrev_b32_e32 v10, 3, v7
	s_and_saveexec_b64 s[4:5], vcc
	s_xor_b64 s[4:5], exec, s[4:5]
	v_lshlrev_b64 v[8:9], 7, v[12:13]
	v_lshl_add_u64 v[8:9], s[28:29], 0, v[8:9]
	v_add_u32_e32 v232, 0xffffff80, v10
	v_lshl_add_u64 v[8:9], v[232:233], 1, v[8:9]
	s_or_saveexec_b64 s[4:5], s[4:5]
	s_lshl_b32 s54, s42, 7
	v_mov_b64_e32 v[166:167], 0x1000
	s_xor_b64 exec, exec, s[4:5]
	v_lshlrev_b64 v[8:9], 10, v[12:13]
	v_lshl_add_u64 v[8:9], s[38:39], 0, v[8:9]
	v_ashrrev_i32_e32 v11, 31, v10
	v_lshl_add_u64 v[8:9], v[10:11], 1, v[8:9]
	v_mov_b64_e32 v[166:167], 0x8000
	s_or_b64 exec, exec, s[4:5]
	v_ashrrev_i32_e32 v7, 3, v2
	v_lshrrev_b32_e32 v2, 4, v2
	v_xor_b32_e32 v2, v2, v14
	v_lshlrev_b32_e32 v2, 4, v2
	s_lshl_b32 s4, s41, 7
	v_and_b32_e32 v232, 0x70, v2
	v_ashrrev_i32_e32 v2, 3, v6
	v_add_u32_e32 v10, s4, v7
	v_add_u32_e32 v6, s4, v2
	v_ashrrev_i32_e32 v11, 31, v10
	v_ashrrev_i32_e32 v7, 31, v6
	s_lshl_b32 s4, s40, 10
	v_lshlrev_b64 v[10:11], 14, v[10:11]
	v_lshlrev_b64 v[6:7], 14, v[6:7]
	s_add_i32 s4, s4, 0
	s_mov_b32 s6, m0
	s_mov_b32 m0, s4
	s_nop 0
	global_load_lds_dwordx4 v[0:1], off
	s_mov_b32 m0, s6
	v_lshl_add_u64 v[10:11], s[14:15], 0, v[10:11]
	v_lshl_add_u64 v[6:7], s[14:15], 0, v[6:7]
	s_add_i32 s6, s4, 0x2000
	s_mov_b32 s7, m0
	s_mov_b32 m0, s6
	s_nop 0
	global_load_lds_dwordx4 v[4:5], off
	s_mov_b32 m0, s7
	v_lshl_add_u64 v[48:49], v[10:11], 0, v[232:233]
	v_lshl_add_u64 v[50:51], v[6:7], 0, v[232:233]
	s_add_i32 s6, s4, 0x4000
	s_mov_b32 s7, m0
	s_mov_b32 m0, s6
	s_nop 0
	global_load_lds_dwordx4 v[8:9], off
	s_mov_b32 m0, s7
	v_lshlrev_b32_e32 v232, 1, v162
	v_lshl_add_u64 v[0:1], v[0:1], 0, v[232:233]
	v_lshlrev_b32_e32 v52, 1, v164
	v_mov_b32_e32 v53, v233
	s_add_i32 s6, s4, 0x6000
	s_mov_b32 s7, m0
	s_mov_b32 m0, s6
	s_nop 0
	global_load_lds_dwordx4 v[0:1], off
	s_mov_b32 m0, s7
	v_lshrrev_b32_e32 v2, 1, v14
; #define LAS __attribute__((address_space(3)))
; #define MFMA32(a, b, c) __builtin_amdgcn_mfma_f32_32x32x16_bf16((a), (b), (c), 0, 0, 0)
; #define ATT_DMA_K(slotoff) do { _Pragma("unroll") for (int n = 0; n < NKI; ++n) glds16(kp[n], (unsigned)__builtin_amdgcn_readfirstlane(kdma + (slotoff) + n * 8192)); } while (0)
; #define ATT_DMA_V(slotoff) do { _Pragma("unroll") for (int n = 0; n < 2; ++n) glds16(vp[n], (unsigned)__builtin_amdgcn_readfirstlane(vdma + (slotoff) + n * 8192)); } while (0)
;     constexpr int NKS = MODE == 0 ? 12 : 4, RB = MODE == 0 ? 384 : 256;
;     f32x16 z;
; #pragma unroll
;     for (int i = 0; i < 16; ++i) z[i] = 0.f;
; #pragma unroll
;     for (int ks = 0; ks < NKS; ++ks) {
;         const LAS unsigned char* p = kslot + ((ka ^ ((ks & 3) * 32)) + (ks >> 2) * 128);
;         const bf16x8 a0 = *(const LAS bf16x8*)p, a1 = *(const LAS bf16x8*)(p + 32 * RB);
;         if (ks == 0) { s0 = MFMA32(a0, qf[0], z); s1 = MFMA32(a1, qf[0], z); }
;         else { s0 = MFMA32(a0, qf[ks], s0); s1 = MFMA32(a1, qf[ks], s1); }
;     }
; }
; template <int MODE>
; __device__ __forceinline__ void attn_phase(LAS unsigned char* lds, const bf16* Qp, const bf16* Kp, const bf16* KPEp, const bf16* Vtp, bf16* CAT, float lam, int vcu, int G) {
;     ...
;         const bf16* vp[2];
; #pragma unroll
;         for (int n = 0; n < 2; ++n) { const int P = 64 * (wave + 8 * n) + lane, dv = P >> 3, c = (P & 7) ^ ((dv >> 1) & 7); vp[n] = Vtp + ((size_t)(bh * 128 + dv)) * SEQ + c * 8; }
;         const unsigned kdma = lds0 + wave * 1024, vdma = lds0 + 3 * KB + wave * 1024;
;     ...
;         const int ka = MODE == 0 ? r * RB + ((hh ^ ((r >> 1) & 7)) * 16) : r * RB + (((map * 8 + hh) ^ (r & 15)) * 16);
;         const int va = r * 128 + ((hh ^ ((r >> 1) & 7)) * 16);
;         const LAS unsigned char* vring = lds + 3 * KB;
;         f32x16 o[4], S0, S1;
;         bf16x8 pf[4];
; #pragma unroll
;         for (int db = 0; db < 4; ++db)
; #pragma unroll
;             for (int i = 0; i < 16; ++i) o[db][i] = 0.f;
;         float mhat = 0.f, lrun = 0.f, fpend = 1.f; bool havepend = false;
;         ATT_DMA_K(0); ATT_ADV_K(); ATT_DMA_K(KB); ATT_ADV_K(); ATT_DMA_V(0); ATT_ADV_V();
;         asm volatile("s_waitcnt vmcnt(0) lgkmcnt(0)\n\ts_barrier" ::: "memory");
;         int kr = 0, kw = 2 * KB, vr = 2 * VB, vw = VB;
	v_lshl_add_u64 v[80:81], v[4:5], 0, v[52:53]
	v_lshlrev_b32_e32 v54, 1, v166
	v_mov_b32_e32 v55, v233
	s_add_i32 s6, s4, 0x8000
	s_mov_b32 s7, m0
	s_mov_b32 m0, s6
	s_nop 0
	global_load_lds_dwordx4 v[80:81], off
	s_mov_b32 m0, s7
	v_bitop3_b32 v2, v179, v2, 7 bitop3:0x78
	v_lshl_add_u64 v[82:83], v[8:9], 0, v[54:55]
	s_add_i32 s6, s4, 0xa000
	s_mov_b32 s7, m0
	s_mov_b32 m0, s6
	s_nop 0
	global_load_lds_dwordx4 v[82:83], off
	s_mov_b32 m0, s7
	s_add_i32 s5, s4, 0x12000
	v_lshlrev_b32_e32 v2, 4, v2
	v_mul_u32_u24_e32 v68, 0x180, v3
	s_mov_b32 s6, m0
	s_mov_b32 m0, s5
	s_nop 0
	global_load_lds_dwordx4 v[48:49], off
	s_mov_b32 m0, s6
	v_or_b32_e32 v163, v2, v68
	s_add_i32 s6, s4, 0x14000
	s_mov_b32 s7, m0
	s_mov_b32 m0, s6
	s_nop 0
	global_load_lds_dwordx4 v[50:51], off
	s_mov_b32 m0, s7
	v_mov_b32_e32 v168, v0
	v_mov_b32_e32 v169, v1
	v_mov_b32_e32 v170, v80
	v_mov_b32_e32 v171, v81
	v_mov_b32_e32 v172, v82
	v_mov_b32_e32 v173, v83
	v_mov_b32_e32 v174, v48
	v_mov_b32_e32 v175, v49
	v_mov_b32_e32 v176, v50
	v_mov_b32_e32 v177, v51
	v_lshlrev_b32_e32 v186, 1, v162
	v_mov_b32_e32 v187, 0
	v_lshlrev_b32_e32 v188, 1, v164
	v_mov_b32_e32 v189, 0
	v_lshlrev_b32_e32 v190, 1, v166
	v_mov_b32_e32 v191, 0
	v_xor_b32_e32 v165, 32, v163
	v_xor_b32_e32 v167, 64, v163
	v_xor_b32_e32 v180, 0x60, v163
	v_lshl_or_b32 v184, v3, 7, v2
	v_xor_b32_e32 v183, 32, v184
	v_xor_b32_e32 v182, 64, v184
	v_xor_b32_e32 v181, 0x60, v184
	s_mov_b32 s45, m0
	s_mov_b32 s44, 0
	s_mov_b32 s55, 0
	v_lshl_add_u64 v[168:169], v[168:169], 0, v[186:187]
	v_lshl_add_u64 v[170:171], v[170:171], 0, v[188:189]
	v_lshl_add_u64 v[172:173], v[172:173], 0, v[190:191]
	s_movk_i32 s36, 0x80
	v_lshl_add_u64 v[174:175], v[174:175], 0, s[36:37]
	v_lshl_add_u64 v[176:177], v[176:177], 0, s[36:37]
	s_waitcnt vmcnt(0) lgkmcnt(0)
	s_barrier
	v_mov_b32_e32 v248, v163
	v_mov_b32_e32 v249, v165
	v_mov_b32_e32 v250, v167
	v_mov_b32_e32 v251, v180
	ds_read_b128 v[196:199], v248
	ds_read_b128 v[200:203], v249
	ds_read_b128 v[204:207], v250
	ds_read_b128 v[208:211], v251
	ds_read_b128 v[212:215], v248 offset:128
	ds_read_b128 v[216:219], v249 offset:128
	ds_read_b128 v[220:223], v250 offset:128
	ds_read_b128 v[224:227], v251 offset:128
	ds_read_b128 v[228:231], v248 offset:256
	s_waitcnt lgkmcnt(7)
	v_mfma_f32_32x32x16_bf16 v[64:79], v[196:199], v[96:99], 0
	v_mov_b64_e32 v[0:1], 0
	v_mov_b64_e32 v[2:3], 0
	v_mov_b64_e32 v[4:5], 0
	v_mov_b64_e32 v[6:7], 0
	v_mov_b64_e32 v[8:9], 0
	v_mov_b64_e32 v[10:11], 0
	v_mov_b64_e32 v[12:13], 0
	v_mov_b64_e32 v[14:15], 0
	v_mov_b64_e32 v[16:17], 0
	v_mov_b64_e32 v[18:19], 0
	v_mov_b64_e32 v[20:21], 0
	v_mov_b64_e32 v[22:23], 0
	v_mov_b64_e32 v[24:25], 0
	v_mov_b64_e32 v[26:27], 0
	v_mov_b64_e32 v[28:29], 0
	v_mov_b64_e32 v[30:31], 0
	v_mfma_f32_32x32x16_bf16 v[64:79], v[200:203], v[100:103], v[64:79]
	ds_read_b128 v[236:239], v249 offset:256
	v_mov_b64_e32 v[32:33], 0
	v_mov_b64_e32 v[34:35], 0
	v_mov_b64_e32 v[36:37], 0
	v_mov_b64_e32 v[38:39], 0
	v_mov_b64_e32 v[40:41], 0
	v_mov_b64_e32 v[42:43], 0
	v_mov_b64_e32 v[44:45], 0
	v_mov_b64_e32 v[46:47], 0
	v_mov_b64_e32 v[48:49], 0
	v_mov_b64_e32 v[50:51], 0
	v_mov_b64_e32 v[52:53], 0
	v_mov_b64_e32 v[54:55], 0
	v_mov_b64_e32 v[56:57], 0
	v_mov_b64_e32 v[58:59], 0
	v_mov_b64_e32 v[60:61], 0
	v_mov_b64_e32 v[62:63], 0
	s_waitcnt lgkmcnt(6)
	v_mfma_f32_32x32x16_bf16 v[64:79], v[204:207], v[104:107], v[64:79]
	ds_read_b128 v[196:199], v250 offset:256
	s_add_i32 s3, s4, 0xc000
	s_mov_b32 m0, s3
	s_nop 0
	global_load_lds_dwordx4 v[168:169], off
	v_mfma_f32_32x32x16_bf16 v[64:79], v[208:211], v[108:111], v[64:79]
	ds_read_b128 v[200:203], v251 offset:256
	s_addk_i32 s3, 0x2000
	s_mov_b32 m0, s3
	s_nop 0
	global_load_lds_dwordx4 v[170:171], off
	s_waitcnt lgkmcnt(6)
	v_mfma_f32_32x32x16_bf16 v[64:79], v[212:215], v[112:115], v[64:79]
	ds_read_b128 v[204:207], v248 offset:12288
	s_addk_i32 s3, 0x2000
	s_mov_b32 m0, s3
	s_nop 0
	global_load_lds_dwordx4 v[172:173], off
	v_mfma_f32_32x32x16_bf16 v[64:79], v[216:219], v[116:119], v[64:79]
	ds_read_b128 v[208:211], v249 offset:12288
	s_cmp_lt_u32 s55, 125
	s_cbranch_scc0 .Lma_noadv0
	v_lshl_add_u64 v[168:169], v[168:169], 0, v[186:187]
	v_lshl_add_u64 v[170:171], v[170:171], 0, v[188:189]
	v_lshl_add_u64 v[172:173], v[172:173], 0, v[190:191]
;     constexpr int NKS = MODE == 0 ? 12 : 4, RB = MODE == 0 ? 384 : 256;
;     f32x16 z;
; #pragma unroll
;     for (int i = 0; i < 16; ++i) z[i] = 0.f;
; #pragma unroll
;     for (int ks = 0; ks < NKS; ++ks) {
;         const LAS unsigned char* p = kslot + ((ka ^ ((ks & 3) * 32)) + (ks >> 2) * 128);
;         const bf16x8 a0 = *(const LAS bf16x8*)p, a1 = *(const LAS bf16x8*)(p + 32 * RB);
;         if (ks == 0) { s0 = MFMA32(a0, qf[0], z); s1 = MFMA32(a1, qf[0], z); }
;         else { s0 = MFMA32(a0, qf[ks], s0); s1 = MFMA32(a1, qf[ks], s1); }
;     }
; }
; __device__ __forceinline__ float att_rowmax(const f32x16& s0, const f32x16& s1) {
;     float a = fmaxf(fmaxf(s0[0], s0[1]), s1[0]), b = fmaxf(fmaxf(s0[2], s0[3]), s1[1]);
;     a = fmaxf(fmaxf(a, s1[2]), s1[3]);
; #pragma unroll
;     for (int i = 4; i < 16; i += 4) { a = fmaxf(fmaxf(a, s0[i]), s0[i + 1]); b = fmaxf(fmaxf(b, s0[i + 2]), s0[i + 3]); a = fmaxf(fmaxf(a, s1[i]), s1[i + 1]); b = fmaxf(fmaxf(b, s1[i + 2]), s1[i + 3]); }
;     return xor32_max(fmaxf(a, b));
; }
; __device__ __forceinline__ void att_exp(f32x16& s0, f32x16& s1, float mhat, float& lrun, bf16x8 (&pf)[4]) {
;     float p0 = 0.f, p1 = 0.f;
; #pragma unroll
;     for (int i = 0; i < 16; ++i) { s0[i] = __builtin_amdgcn_exp2f(s0[i] - mhat); s1[i] = __builtin_amdgcn_exp2f(s1[i] - mhat); p0 += s0[i]; p1 += s1[i]; }
;     lrun += p0 + p1;
;     pf[0] = pack8((f32x4){s0[0], s0[1], s0[2], s0[3]}, (f32x4){s0[4], s0[5], s0[6], s0[7]});
;     pf[1] = pack8((f32x4){s0[8], s0[9], s0[10], s0[11]}, (f32x4){s0[12], s0[13], s0[14], s0[15]});
;     pf[2] = pack8((f32x4){s1[0], s1[1], s1[2], s1[3]}, (f32x4){s1[4], s1[5], s1[6], s1[7]});
;     pf[3] = pack8((f32x4){s1[8], s1[9], s1[10], s1[11]}, (f32x4){s1[12], s1[13], s1[14], s1[15]});
; }
; template <int MODE>
; __device__ __forceinline__ void attn_phase(LAS unsigned char* lds, const bf16* Qp, const bf16* Kp, const bf16* KPEp, const bf16* Vtp, bf16* CAT, float lam, int vcu, int G) {
;     ...
;         for (int i = 0; i < 128; ++i) {
;             att_qk<MODE>(S0, S1, lds + kr, ka, qf);
;             const float rm = att_rowmax(S0, S1);
;             if (i == 0) mhat = rm;
;             else if (__any(rm - mhat > THR)) { const float dl = fmaxf(rm - mhat, 0.f), f = __builtin_amdgcn_exp2f(-dl); lrun *= f; mhat += dl; fpend = f; havepend = true; }
;             if (i > 0) att_pv(o, vring + vr, va, pf);
.Lma_noadv0:
	s_waitcnt lgkmcnt(6)
	v_mfma_f32_32x32x16_bf16 v[64:79], v[220:223], v[120:123], v[64:79]
	ds_read_b128 v[212:215], v250 offset:12288
	s_add_i32 s3, s4, 0x16000
	s_mov_b32 m0, s3
	s_nop 0
	global_load_lds_dwordx4 v[174:175], off
	v_mfma_f32_32x32x16_bf16 v[64:79], v[224:227], v[124:127], v[64:79]
	ds_read_b128 v[216:219], v251 offset:12288
	s_addk_i32 s3, 0x2000
	s_mov_b32 m0, s3
	s_nop 0
	global_load_lds_dwordx4 v[176:177], off
	s_waitcnt lgkmcnt(6)
	v_mfma_f32_32x32x16_bf16 v[64:79], v[228:231], v[128:131], v[64:79]
	ds_read_b128 v[220:223], v248 offset:12416
	s_cmp_lt_u32 s55, 126
	s_cselect_b32 s36, 0x80, 0
	v_lshl_add_u64 v[174:175], v[174:175], 0, s[36:37]
	v_lshl_add_u64 v[176:177], v[176:177], 0, s[36:37]
	v_mfma_f32_32x32x16_bf16 v[64:79], v[236:239], v[132:135], v[64:79]
	ds_read_b128 v[224:227], v249 offset:12416
	s_waitcnt lgkmcnt(6)
	v_mfma_f32_32x32x16_bf16 v[64:79], v[196:199], v[136:139], v[64:79]
	ds_read_b128 v[228:231], v250 offset:12416
	v_mfma_f32_32x32x16_bf16 v[64:79], v[200:203], v[140:143], v[64:79]
	ds_read_b128 v[236:239], v251 offset:12416
	s_waitcnt lgkmcnt(6)
	v_mfma_f32_32x32x16_bf16 v[80:95], v[204:207], v[96:99], 0
	ds_read_b128 v[196:199], v248 offset:12544
	v_mfma_f32_32x32x16_bf16 v[80:95], v[208:211], v[100:103], v[80:95]
	ds_read_b128 v[200:203], v249 offset:12544
	s_waitcnt lgkmcnt(6)
	v_mfma_f32_32x32x16_bf16 v[80:95], v[212:215], v[104:107], v[80:95]
	ds_read_b128 v[204:207], v250 offset:12544
	v_mfma_f32_32x32x16_bf16 v[80:95], v[216:219], v[108:111], v[80:95]
	ds_read_b128 v[208:211], v251 offset:12544
	s_waitcnt lgkmcnt(6)
	v_mfma_f32_32x32x16_bf16 v[80:95], v[220:223], v[112:115], v[80:95]
	v_mfma_f32_32x32x16_bf16 v[80:95], v[224:227], v[116:119], v[80:95]
	s_waitcnt lgkmcnt(4)
	v_mfma_f32_32x32x16_bf16 v[80:95], v[228:231], v[120:123], v[80:95]
	v_mfma_f32_32x32x16_bf16 v[80:95], v[236:239], v[124:127], v[80:95]
	s_waitcnt lgkmcnt(2)
	v_mfma_f32_32x32x16_bf16 v[80:95], v[196:199], v[128:131], v[80:95]
	v_mfma_f32_32x32x16_bf16 v[80:95], v[200:203], v[132:135], v[80:95]
	s_waitcnt lgkmcnt(0)
	v_mfma_f32_32x32x16_bf16 v[80:95], v[204:207], v[136:139], v[80:95]
	v_mfma_f32_32x32x16_bf16 v[80:95], v[208:211], v[140:143], v[80:95]
	s_nop 15
	s_nop 15
	v_max3_f32 v194, v64, v65, v66
	v_max3_f32 v195, v67, v68, v69
	v_max3_f32 v194, v194, v70, v71
	v_max3_f32 v195, v195, v72, v73
	v_max3_f32 v194, v194, v74, v75
	v_max3_f32 v195, v195, v76, v77
	v_max3_f32 v194, v194, v78, v79
	v_max3_f32 v194, v194, v80, v81
	v_max3_f32 v195, v195, v82, v83
	v_max3_f32 v194, v194, v84, v85
	v_max3_f32 v195, v195, v86, v87
	v_max3_f32 v194, v194, v88, v89
	v_max3_f32 v195, v195, v90, v91
	v_max3_f32 v194, v194, v92, v93
	v_max3_f32 v195, v195, v94, v95
	v_max_f32_e32 v194, v194, v195
	v_mov_b32_e32 v195, v194
	s_nop 1
	v_permlane32_swap_b32_e32 v194, v195
	v_max_f32_e32 v194, v194, v195
	v_mov_b32_e32 v243, v194
	v_mov_b32_e32 v192, 0
	v_mov_b32_e32 v193, 0
	v_sub_f32_e32 v64, v64, v243
	v_sub_f32_e32 v65, v65, v243
	v_exp_f32_e32 v64, v64
	v_exp_f32_e32 v65, v65
	v_add_f32_e32 v192, v192, v64
	v_add_f32_e32 v193, v193, v65
	v_sub_f32_e32 v66, v66, v243
	v_sub_f32_e32 v67, v67, v243
	v_exp_f32_e32 v66, v66
	v_exp_f32_e32 v67, v67
	v_add_f32_e32 v192, v192, v66
	v_add_f32_e32 v193, v193, v67
	v_sub_f32_e32 v68, v68, v243
	v_sub_f32_e32 v69, v69, v243
	v_exp_f32_e32 v68, v68
	v_exp_f32_e32 v69, v69
	v_add_f32_e32 v192, v192, v68
	v_add_f32_e32 v193, v193, v69
	v_sub_f32_e32 v70, v70, v243
	v_sub_f32_e32 v71, v71, v243
	v_exp_f32_e32 v70, v70
	v_exp_f32_e32 v71, v71
	v_add_f32_e32 v192, v192, v70
	v_add_f32_e32 v193, v193, v71
	v_sub_f32_e32 v72, v72, v243
	v_sub_f32_e32 v73, v73, v243
	v_exp_f32_e32 v72, v72
	v_exp_f32_e32 v73, v73
	v_add_f32_e32 v192, v192, v72
	v_add_f32_e32 v193, v193, v73
	v_sub_f32_e32 v74, v74, v243
	v_sub_f32_e32 v75, v75, v243
	v_exp_f32_e32 v74, v74
	v_exp_f32_e32 v75, v75
	v_add_f32_e32 v192, v192, v74
	v_add_f32_e32 v193, v193, v75
	v_sub_f32_e32 v76, v76, v243
	v_sub_f32_e32 v77, v77, v243
	v_exp_f32_e32 v76, v76
	v_exp_f32_e32 v77, v77
	v_add_f32_e32 v192, v192, v76
	v_add_f32_e32 v193, v193, v77
	v_sub_f32_e32 v78, v78, v243
	v_sub_f32_e32 v79, v79, v243
	v_exp_f32_e32 v78, v78
	v_exp_f32_e32 v79, v79
	v_add_f32_e32 v192, v192, v78
	v_add_f32_e32 v193, v193, v79
	v_cvt_pk_bf16_f32 v144, v64, v65
	v_cvt_pk_bf16_f32 v145, v66, v67
	v_cvt_pk_bf16_f32 v146, v68, v69
	v_cvt_pk_bf16_f32 v147, v70, v71
	v_cvt_pk_bf16_f32 v148, v72, v73
	v_cvt_pk_bf16_f32 v149, v74, v75
	v_cvt_pk_bf16_f32 v150, v76, v77
	v_cvt_pk_bf16_f32 v151, v78, v79
	s_mov_b32 s55, 1
	s_movk_i32 s38, 0x6000
	s_mov_b32 s39, 0
	s_mov_b32 s40, 0xc000
	s_mov_b32 s41, 0x16000
	s_mov_b32 s42, 0x12000
	s_mov_b32 s43, 0x1a000
	s_waitcnt vmcnt(5) lgkmcnt(0)
	s_barrier
;     constexpr int NKS = MODE == 0 ? 12 : 4, RB = MODE == 0 ? 384 : 256;
;     f32x16 z;
; #pragma unroll
;     for (int i = 0; i < 16; ++i) z[i] = 0.f;
; #pragma unroll
;     for (int ks = 0; ks < NKS; ++ks) {
;         const LAS unsigned char* p = kslot + ((ka ^ ((ks & 3) * 32)) + (ks >> 2) * 128);
;         const bf16x8 a0 = *(const LAS bf16x8*)p, a1 = *(const LAS bf16x8*)(p + 32 * RB);
;         if (ks == 0) { s0 = MFMA32(a0, qf[0], z); s1 = MFMA32(a1, qf[0], z); }
;         else { s0 = MFMA32(a0, qf[ks], s0); s1 = MFMA32(a1, qf[ks], s1); }
;     }
; }
; __device__ __forceinline__ float att_rowmax(const f32x16& s0, const f32x16& s1) {
;     float a = fmaxf(fmaxf(s0[0], s0[1]), s1[0]), b = fmaxf(fmaxf(s0[2], s0[3]), s1[1]);
;     a = fmaxf(fmaxf(a, s1[2]), s1[3]);
; #pragma unroll
;     for (int i = 4; i < 16; i += 4) { a = fmaxf(fmaxf(a, s0[i]), s0[i + 1]); b = fmaxf(fmaxf(b, s0[i + 2]), s0[i + 3]); a = fmaxf(fmaxf(a, s1[i]), s1[i + 1]); b = fmaxf(fmaxf(b, s1[i + 2]), s1[i + 3]); }
;     return xor32_max(fmaxf(a, b));
; }
; __device__ __forceinline__ void att_exp(f32x16& s0, f32x16& s1, float mhat, float& lrun, bf16x8 (&pf)[4]) {
;     float p0 = 0.f, p1 = 0.f;
; #pragma unroll
;     for (int i = 0; i < 16; ++i) { s0[i] = __builtin_amdgcn_exp2f(s0[i] - mhat); s1[i] = __builtin_amdgcn_exp2f(s1[i] - mhat); p0 += s0[i]; p1 += s1[i]; }
;     lrun += p0 + p1;
;     pf[0] = pack8((f32x4){s0[0], s0[1], s0[2], s0[3]}, (f32x4){s0[4], s0[5], s0[6], s0[7]});
;     pf[1] = pack8((f32x4){s0[8], s0[9], s0[10], s0[11]}, (f32x4){s0[12], s0[13], s0[14], s0[15]});
;     pf[2] = pack8((f32x4){s1[0], s1[1], s1[2], s1[3]}, (f32x4){s1[4], s1[5], s1[6], s1[7]});
;     pf[3] = pack8((f32x4){s1[8], s1[9], s1[10], s1[11]}, (f32x4){s1[12], s1[13], s1[14], s1[15]});
; }
; template <int MODE>
; __device__ __forceinline__ void attn_phase(LAS unsigned char* lds, const bf16* Qp, const bf16* Kp, const bf16* KPEp, const bf16* Vtp, bf16* CAT, float lam, int vcu, int G) {
;     ...
;         for (int i = 0; i < 128; ++i) {
;             att_qk<MODE>(S0, S1, lds + kr, ka, qf);
;             const float rm = att_rowmax(S0, S1);
;             if (i == 0) mhat = rm;
;             else if (__any(rm - mhat > THR)) { const float dl = fmaxf(rm - mhat, 0.f), f = __builtin_amdgcn_exp2f(-dl); lrun *= f; mhat += dl; fpend = f; havepend = true; }
;             if (i > 0) att_pv(o, vring + vr, va, pf);
.Lma_loop:
	v_add_u32_e32 v248, s38, v163
	v_add_u32_e32 v249, s38, v165
	v_add_u32_e32 v250, s38, v167
	v_add_u32_e32 v251, s38, v180
	v_add_u32_e32 v244, s42, v184
	v_add_u32_e32 v245, s42, v183
	v_add_u32_e32 v246, s42, v182
	v_add_u32_e32 v247, s42, v181
	ds_read_b128 v[196:199], v248
	ds_read_b128 v[200:203], v249
	ds_read_b128 v[204:207], v250
	ds_read_b128 v[208:211], v251
	ds_read_b128 v[212:215], v248 offset:128
	ds_read_b128 v[216:219], v249 offset:128
	ds_read_b128 v[220:223], v250 offset:128
	ds_read_b128 v[224:227], v251 offset:128
	ds_read_b128 v[228:231], v248 offset:256
	s_waitcnt lgkmcnt(7)
	v_mfma_f32_32x32x16_bf16 v[64:79], v[196:199], v[96:99], 0
	v_sub_f32_e32 v80, v80, v243
	v_sub_f32_e32 v81, v81, v243
	v_exp_f32_e32 v80, v80
	v_exp_f32_e32 v81, v81
	v_add_f32_e32 v192, v192, v80
	v_add_f32_e32 v193, v193, v81
	v_mfma_f32_32x32x16_bf16 v[64:79], v[200:203], v[100:103], v[64:79]
	ds_read_b128 v[236:239], v249 offset:256
	v_sub_f32_e32 v82, v82, v243
	v_sub_f32_e32 v83, v83, v243
	v_exp_f32_e32 v82, v82
	v_exp_f32_e32 v83, v83
	v_add_f32_e32 v192, v192, v82
	v_add_f32_e32 v193, v193, v83
	s_waitcnt lgkmcnt(6)
	v_mfma_f32_32x32x16_bf16 v[64:79], v[204:207], v[104:107], v[64:79]
	ds_read_b128 v[196:199], v250 offset:256
	v_sub_f32_e32 v84, v84, v243
	v_sub_f32_e32 v85, v85, v243
	v_exp_f32_e32 v84, v84
	v_exp_f32_e32 v85, v85
	v_add_f32_e32 v192, v192, v84
	v_add_f32_e32 v193, v193, v85
	v_mfma_f32_32x32x16_bf16 v[64:79], v[208:211], v[108:111], v[64:79]
	ds_read_b128 v[200:203], v251 offset:256
	v_sub_f32_e32 v86, v86, v243
	v_sub_f32_e32 v87, v87, v243
	v_exp_f32_e32 v86, v86
	v_exp_f32_e32 v87, v87
	v_add_f32_e32 v192, v192, v86
	v_add_f32_e32 v193, v193, v87
	s_waitcnt lgkmcnt(6)
	v_mfma_f32_32x32x16_bf16 v[64:79], v[212:215], v[112:115], v[64:79]
	ds_read_b128 v[204:207], v248 offset:12288
	v_sub_f32_e32 v88, v88, v243
	v_sub_f32_e32 v89, v89, v243
	v_exp_f32_e32 v88, v88
	v_exp_f32_e32 v89, v89
	v_add_f32_e32 v192, v192, v88
	v_add_f32_e32 v193, v193, v89
	v_mfma_f32_32x32x16_bf16 v[64:79], v[216:219], v[116:119], v[64:79]
	ds_read_b128 v[208:211], v249 offset:12288
	v_sub_f32_e32 v90, v90, v243
	v_sub_f32_e32 v91, v91, v243
	v_exp_f32_e32 v90, v90
	v_exp_f32_e32 v91, v91
	v_add_f32_e32 v192, v192, v90
	v_add_f32_e32 v193, v193, v91
	v_cvt_pk_bf16_f32 v152, v80, v81
	v_cvt_pk_bf16_f32 v153, v82, v83
	s_waitcnt lgkmcnt(6)
	v_mfma_f32_32x32x16_bf16 v[64:79], v[220:223], v[120:123], v[64:79]
	ds_read_b128 v[212:215], v250 offset:12288
	v_sub_f32_e32 v92, v92, v243
	v_sub_f32_e32 v93, v93, v243
	v_exp_f32_e32 v92, v92
	v_exp_f32_e32 v93, v93
	v_add_f32_e32 v192, v192, v92
	v_add_f32_e32 v193, v193, v93
	v_cvt_pk_bf16_f32 v154, v84, v85
	v_cvt_pk_bf16_f32 v155, v86, v87
	v_mfma_f32_32x32x16_bf16 v[64:79], v[224:227], v[124:127], v[64:79]
	ds_read_b128 v[216:219], v251 offset:12288
	v_sub_f32_e32 v94, v94, v243
	v_sub_f32_e32 v95, v95, v243
	v_exp_f32_e32 v94, v94
	v_exp_f32_e32 v95, v95
	v_add_f32_e32 v192, v192, v94
	v_add_f32_e32 v193, v193, v95
	s_waitcnt lgkmcnt(6)
	v_mfma_f32_32x32x16_bf16 v[64:79], v[228:231], v[128:131], v[64:79]
	ds_read_b128 v[220:223], v248 offset:12416
	v_mfma_f32_32x32x16_bf16 v[64:79], v[236:239], v[132:135], v[64:79]
	ds_read_b128 v[224:227], v249 offset:12416
	v_cvt_pk_bf16_f32 v156, v88, v89
	v_cvt_pk_bf16_f32 v157, v90, v91
	s_waitcnt lgkmcnt(6)
	v_mfma_f32_32x32x16_bf16 v[64:79], v[196:199], v[136:139], v[64:79]
	ds_read_b128 v[228:231], v250 offset:12416
	v_cvt_pk_bf16_f32 v158, v92, v93
	v_cvt_pk_bf16_f32 v159, v94, v95
	v_mfma_f32_32x32x16_bf16 v[64:79], v[200:203], v[140:143], v[64:79]
	ds_read_b128 v[236:239], v251 offset:12416
	s_waitcnt lgkmcnt(6)
	v_mfma_f32_32x32x16_bf16 v[80:95], v[204:207], v[96:99], 0
	ds_read_b128 v[196:199], v248 offset:12544
	v_mfma_f32_32x32x16_bf16 v[80:95], v[208:211], v[100:103], v[80:95]
	ds_read_b128 v[200:203], v249 offset:12544
	s_add_i32 s3, s4, s39
	s_mov_b32 m0, s3
	s_nop 0
	global_load_lds_dwordx4 v[168:169], off
	s_waitcnt lgkmcnt(6)
	v_mfma_f32_32x32x16_bf16 v[80:95], v[212:215], v[104:107], v[80:95]
	ds_read_b128 v[204:207], v250 offset:12544
	s_addk_i32 s3, 0x2000
	s_mov_b32 m0, s3
	s_nop 0
	global_load_lds_dwordx4 v[170:171], off
	v_mfma_f32_32x32x16_bf16 v[80:95], v[216:219], v[108:111], v[80:95]
	ds_read_b128 v[208:211], v251 offset:12544
	s_addk_i32 s3, 0x2000
	s_mov_b32 m0, s3
	s_nop 0
	global_load_lds_dwordx4 v[172:173], off
	s_waitcnt lgkmcnt(6)
	v_mfma_f32_32x32x16_bf16 v[80:95], v[220:223], v[112:115], v[80:95]
	ds_read_b128 v[212:215], v244
	s_cmp_lt_u32 s55, 125
	s_cbranch_scc0 .Lma_noadv1
	v_lshl_add_u64 v[168:169], v[168:169], 0, v[186:187]
	v_lshl_add_u64 v[170:171], v[170:171], 0, v[188:189]
	v_lshl_add_u64 v[172:173], v[172:173], 0, v[190:191]
; #define LAS __attribute__((address_space(3)))
; __device__ __forceinline__ float att_rowmax(const f32x16& s0, const f32x16& s1) {
;     float a = fmaxf(fmaxf(s0[0], s0[1]), s1[0]), b = fmaxf(fmaxf(s0[2], s0[3]), s1[1]);
;     a = fmaxf(fmaxf(a, s1[2]), s1[3]);
; #pragma unroll
;     for (int i = 4; i < 16; i += 4) { a = fmaxf(fmaxf(a, s0[i]), s0[i + 1]); b = fmaxf(fmaxf(b, s0[i + 2]), s0[i + 3]); a = fmaxf(fmaxf(a, s1[i]), s1[i + 1]); b = fmaxf(fmaxf(b, s1[i + 2]), s1[i + 3]); }
;     return xor32_max(fmaxf(a, b));
; }
; __device__ __forceinline__ void att_exp(f32x16& s0, f32x16& s1, float mhat, float& lrun, bf16x8 (&pf)[4]) {
;     float p0 = 0.f, p1 = 0.f;
; #pragma unroll
;     for (int i = 0; i < 16; ++i) { s0[i] = __builtin_amdgcn_exp2f(s0[i] - mhat); s1[i] = __builtin_amdgcn_exp2f(s1[i] - mhat); p0 += s0[i]; p1 += s1[i]; }
;     lrun += p0 + p1;
;     pf[0] = pack8((f32x4){s0[0], s0[1], s0[2], s0[3]}, (f32x4){s0[4], s0[5], s0[6], s0[7]});
;     pf[1] = pack8((f32x4){s0[8], s0[9], s0[10], s0[11]}, (f32x4){s0[12], s0[13], s0[14], s0[15]});
;     pf[2] = pack8((f32x4){s1[0], s1[1], s1[2], s1[3]}, (f32x4){s1[4], s1[5], s1[6], s1[7]});
;     pf[3] = pack8((f32x4){s1[8], s1[9], s1[10], s1[11]}, (f32x4){s1[12], s1[13], s1[14], s1[15]});
; }
; __device__ __forceinline__ void att_pv(f32x16 (&o)[4], const LAS unsigned char* vslot, int va, const bf16x8 (&pf)[4]) {
; #pragma unroll
;     for (int db = 0; db < 4; ++db)
; #pragma unroll
;         for (int kk = 0; kk < 4; ++kk) {
;             const bf16x8 v = *(const LAS bf16x8*)(vslot + ((va ^ (kk * 32)) + db * 4096));
;             o[db] = MFMA32(v, pf[kk], o[db]);
;         }
; }
; template <int MODE>
; __device__ __forceinline__ void attn_phase(LAS unsigned char* lds, const bf16* Qp, const bf16* Kp, const bf16* KPEp, const bf16* Vtp, bf16* CAT, float lam, int vcu, int G) {
;     ...
;             const float rm = att_rowmax(S0, S1);
;             if (i == 0) mhat = rm;
;             else if (__any(rm - mhat > THR)) { const float dl = fmaxf(rm - mhat, 0.f), f = __builtin_amdgcn_exp2f(-dl); lrun *= f; mhat += dl; fpend = f; havepend = true; }
;             if (i > 0) att_pv(o, vring + vr, va, pf);
;             att_exp(S0, S1, mhat, lrun, pf);
;             ATT_RESC_O();
;             ATT_DMA_K(kw); ATT_DMA_V(vw);
;             if (i + 2 < 127) ATT_ADV_K();
;             if (i + 1 < 127) ATT_ADV_V();
.Lma_noadv1:
	v_mfma_f32_32x32x16_bf16 v[80:95], v[224:227], v[116:119], v[80:95]
	ds_read_b128 v[216:219], v244 offset:4096
	s_add_i32 s3, s4, s43
	s_mov_b32 m0, s3
	s_nop 0
	global_load_lds_dwordx4 v[174:175], off
	s_waitcnt lgkmcnt(6)
	v_mfma_f32_32x32x16_bf16 v[80:95], v[228:231], v[120:123], v[80:95]
	ds_read_b128 v[220:223], v244 offset:8192
	s_addk_i32 s3, 0x2000
	s_mov_b32 m0, s3
	s_nop 0
	global_load_lds_dwordx4 v[176:177], off
	v_mfma_f32_32x32x16_bf16 v[80:95], v[236:239], v[124:127], v[80:95]
	ds_read_b128 v[224:227], v244 offset:12288
	s_cmp_lt_u32 s55, 126
	s_cselect_b32 s36, 0x80, 0
	v_lshl_add_u64 v[174:175], v[174:175], 0, s[36:37]
	v_lshl_add_u64 v[176:177], v[176:177], 0, s[36:37]
	s_waitcnt lgkmcnt(6)
	v_mfma_f32_32x32x16_bf16 v[80:95], v[196:199], v[128:131], v[80:95]
	ds_read_b128 v[228:231], v245
	v_max3_f32 v194, v64, v65, v66
	v_max3_f32 v195, v67, v68, v69
	v_max3_f32 v194, v194, v70, v71
	v_max3_f32 v195, v195, v72, v73
	v_mfma_f32_32x32x16_bf16 v[80:95], v[200:203], v[132:135], v[80:95]
	ds_read_b128 v[236:239], v245 offset:4096
	v_max3_f32 v194, v194, v74, v75
	v_max3_f32 v195, v195, v76, v77
	v_max3_f32 v194, v194, v78, v79
	s_waitcnt lgkmcnt(6)
	v_mfma_f32_32x32x16_bf16 v[80:95], v[204:207], v[136:139], v[80:95]
	ds_read_b128 v[196:199], v245 offset:8192
	v_mfma_f32_32x32x16_bf16 v[80:95], v[208:211], v[140:143], v[80:95]
	ds_read_b128 v[200:203], v245 offset:12288
	s_waitcnt lgkmcnt(6)
	v_mfma_f32_32x32x16_bf16 v[48:63], v[212:215], v[144:147], v[48:63]
	ds_read_b128 v[204:207], v246
	v_mfma_f32_32x32x16_bf16 v[32:47], v[216:219], v[144:147], v[32:47]
	ds_read_b128 v[208:211], v246 offset:4096
	s_waitcnt lgkmcnt(6)
	v_mfma_f32_32x32x16_bf16 v[16:31], v[220:223], v[144:147], v[16:31]
	ds_read_b128 v[212:215], v246 offset:8192
	v_mfma_f32_32x32x16_bf16 v[0:15], v[224:227], v[144:147], v[0:15]
	ds_read_b128 v[216:219], v246 offset:12288
	s_waitcnt lgkmcnt(6)
	v_mfma_f32_32x32x16_bf16 v[48:63], v[228:231], v[148:151], v[48:63]
	ds_read_b128 v[220:223], v247
	v_max3_f32 v194, v194, v80, v81
	v_max3_f32 v195, v195, v82, v83
	v_max3_f32 v194, v194, v84, v85
	v_max3_f32 v195, v195, v86, v87
	v_mfma_f32_32x32x16_bf16 v[32:47], v[236:239], v[148:151], v[32:47]
	ds_read_b128 v[224:227], v247 offset:4096
	v_max3_f32 v194, v194, v88, v89
	v_max3_f32 v195, v195, v90, v91
	v_max3_f32 v194, v194, v92, v93
	v_max3_f32 v195, v195, v94, v95
	v_max_f32_e32 v194, v194, v195
	v_mov_b32_e32 v195, v194
	s_nop 1
	v_permlane32_swap_b32_e32 v194, v195
	v_max_f32_e32 v194, v194, v195
	v_sub_f32_e32 v242, v194, v243
	v_cmp_lt_f32_e32 vcc, 0x41000000, v242
	s_waitcnt lgkmcnt(6)
	v_mfma_f32_32x32x16_bf16 v[16:31], v[196:199], v[148:151], v[16:31]
	ds_read_b128 v[228:231], v247 offset:8192
	s_nop 1
	s_cmp_lg_u64 vcc, 0
	s_cbranch_scc1 .Lma_rareA
.Lma_backA:
	v_sub_f32_e32 v64, v64, v243
	v_sub_f32_e32 v65, v65, v243
	v_exp_f32_e32 v64, v64
	v_exp_f32_e32 v65, v65
	v_add_f32_e32 v192, v192, v64
	v_add_f32_e32 v193, v193, v65
	v_mfma_f32_32x32x16_bf16 v[0:15], v[200:203], v[148:151], v[0:15]
	ds_read_b128 v[236:239], v247 offset:12288
	v_sub_f32_e32 v66, v66, v243
	v_sub_f32_e32 v67, v67, v243
	v_exp_f32_e32 v66, v66
	v_exp_f32_e32 v67, v67
	v_add_f32_e32 v192, v192, v66
	v_add_f32_e32 v193, v193, v67
	s_waitcnt lgkmcnt(6)
	v_mfma_f32_32x32x16_bf16 v[48:63], v[204:207], v[152:155], v[48:63]
	v_sub_f32_e32 v68, v68, v243
	v_sub_f32_e32 v69, v69, v243
	v_exp_f32_e32 v68, v68
	v_exp_f32_e32 v69, v69
	v_add_f32_e32 v192, v192, v68
	v_add_f32_e32 v193, v193, v69
	v_mfma_f32_32x32x16_bf16 v[32:47], v[208:211], v[152:155], v[32:47]
	v_sub_f32_e32 v70, v70, v243
	v_sub_f32_e32 v71, v71, v243
	v_exp_f32_e32 v70, v70
	v_exp_f32_e32 v71, v71
	v_add_f32_e32 v192, v192, v70
	v_add_f32_e32 v193, v193, v71
	v_cvt_pk_bf16_f32 v144, v64, v65
	v_cvt_pk_bf16_f32 v145, v66, v67
	s_waitcnt lgkmcnt(4)
	v_mfma_f32_32x32x16_bf16 v[16:31], v[212:215], v[152:155], v[16:31]
	v_sub_f32_e32 v72, v72, v243
	v_sub_f32_e32 v73, v73, v243
	v_exp_f32_e32 v72, v72
	v_exp_f32_e32 v73, v73
	v_add_f32_e32 v192, v192, v72
	v_add_f32_e32 v193, v193, v73
	v_cvt_pk_bf16_f32 v146, v68, v69
	v_cvt_pk_bf16_f32 v147, v70, v71
	v_mfma_f32_32x32x16_bf16 v[0:15], v[216:219], v[152:155], v[0:15]
	v_sub_f32_e32 v74, v74, v243
	v_sub_f32_e32 v75, v75, v243
	v_exp_f32_e32 v74, v74
	v_exp_f32_e32 v75, v75
	v_add_f32_e32 v192, v192, v74
	v_add_f32_e32 v193, v193, v75
	s_waitcnt lgkmcnt(2)
	v_mfma_f32_32x32x16_bf16 v[48:63], v[220:223], v[156:159], v[48:63]
	v_sub_f32_e32 v76, v76, v243
	v_sub_f32_e32 v77, v77, v243
	v_exp_f32_e32 v76, v76
	v_exp_f32_e32 v77, v77
	v_add_f32_e32 v192, v192, v76
	v_add_f32_e32 v193, v193, v77
	v_mfma_f32_32x32x16_bf16 v[32:47], v[224:227], v[156:159], v[32:47]
	v_sub_f32_e32 v78, v78, v243
	v_sub_f32_e32 v79, v79, v243
	v_exp_f32_e32 v78, v78
	v_exp_f32_e32 v79, v79
	v_add_f32_e32 v192, v192, v78
	v_add_f32_e32 v193, v193, v79
	s_waitcnt lgkmcnt(0)
	v_mfma_f32_32x32x16_bf16 v[16:31], v[228:231], v[156:159], v[16:31]
	v_cvt_pk_bf16_f32 v148, v72, v73
	v_cvt_pk_bf16_f32 v149, v74, v75
	v_mfma_f32_32x32x16_bf16 v[0:15], v[236:239], v[156:159], v[0:15]
	v_cvt_pk_bf16_f32 v150, v76, v77
	v_cvt_pk_bf16_f32 v151, v78, v79
	s_cmp_eq_u32 s44, 0
	s_cbranch_scc1 .Lma_skipB
; #define ATT_DMA_K(slotoff) do { _Pragma("unroll") for (int n = 0; n < NKI; ++n) glds16(kp[n], (unsigned)__builtin_amdgcn_readfirstlane(kdma + (slotoff) + n * 8192)); } while (0)
; #define ATT_DMA_V(slotoff) do { _Pragma("unroll") for (int n = 0; n < 2; ++n) glds16(vp[n], (unsigned)__builtin_amdgcn_readfirstlane(vdma + (slotoff) + n * 8192)); } while (0)
; #define ATT_ADV_K() do { _Pragma("unroll") for (int n = 0; n < NKI; ++n) kp[n] += kadv[n]; } while (0)
; #define ATT_ADV_V() do { _Pragma("unroll") for (int n = 0; n < 2; ++n) vp[n] += 64; } while (0)
; #define ATT_RESC_O() do { if (havepend) { _Pragma("unroll") for (int db = 0; db < 4; ++db) _Pragma("unroll") for (int i = 0; i < 16; ++i) o[db][i] *= fpend; havepend = false; } } while (0)
; template <int MODE>
; __device__ __forceinline__ void attn_phase(LAS unsigned char* lds, const bf16* Qp, const bf16* Kp, const bf16* KPEp, const bf16* Vtp, bf16* CAT, float lam, int vcu, int G) {
;     ...
;             else if (__any(rm - mhat > THR)) { const float dl = fmaxf(rm - mhat, 0.f), f = __builtin_amdgcn_exp2f(-dl); lrun *= f; mhat += dl; fpend = f; havepend = true; }
;             if (i > 0) att_pv(o, vring + vr, va, pf);
;             att_exp(S0, S1, mhat, lrun, pf);
;             ATT_RESC_O();
;             ATT_DMA_K(kw); ATT_DMA_V(vw);
;             if (i + 2 < 127) ATT_ADV_K();
;             if (i + 1 < 127) ATT_ADV_V();
;             kr = (kr == 2 * KB) ? 0 : kr + KB; kw = (kw == 2 * KB) ? 0 : kw + KB;
;             vr = (vr == 2 * VB) ? 0 : vr + VB; vw = (vw == 2 * VB) ? 0 : vw + VB;
;             asm volatile("s_waitcnt vmcnt(5) lgkmcnt(0)\n\ts_barrier" ::: "memory");
;         }
;         }
;         att_pv(o, vring + vr, va, pf);
;         asm volatile("s_waitcnt vmcnt(0) lgkmcnt(0)\n\ts_barrier" ::: "memory");
	s_nop 11
	v_mul_f32_e32 v0, v241, v0
	v_mul_f32_e32 v1, v241, v1
	v_mul_f32_e32 v2, v241, v2
	v_mul_f32_e32 v3, v241, v3
	v_mul_f32_e32 v4, v241, v4
	v_mul_f32_e32 v5, v241, v5
	v_mul_f32_e32 v6, v241, v6
	v_mul_f32_e32 v7, v241, v7
	v_mul_f32_e32 v8, v241, v8
	v_mul_f32_e32 v9, v241, v9
	v_mul_f32_e32 v10, v241, v10
	v_mul_f32_e32 v11, v241, v11
	v_mul_f32_e32 v12, v241, v12
	v_mul_f32_e32 v13, v241, v13
	v_mul_f32_e32 v14, v241, v14
	v_mul_f32_e32 v15, v241, v15
	v_mul_f32_e32 v16, v241, v16
	v_mul_f32_e32 v17, v241, v17
	v_mul_f32_e32 v18, v241, v18
	v_mul_f32_e32 v19, v241, v19
	v_mul_f32_e32 v20, v241, v20
	v_mul_f32_e32 v21, v241, v21
	v_mul_f32_e32 v22, v241, v22
	v_mul_f32_e32 v23, v241, v23
	v_mul_f32_e32 v24, v241, v24
	v_mul_f32_e32 v25, v241, v25
	v_mul_f32_e32 v26, v241, v26
	v_mul_f32_e32 v27, v241, v27
	v_mul_f32_e32 v28, v241, v28
	v_mul_f32_e32 v29, v241, v29
	v_mul_f32_e32 v30, v241, v30
	v_mul_f32_e32 v31, v241, v31
	v_mul_f32_e32 v32, v241, v32
	v_mul_f32_e32 v33, v241, v33
	v_mul_f32_e32 v34, v241, v34
	v_mul_f32_e32 v35, v241, v35
	v_mul_f32_e32 v36, v241, v36
	v_mul_f32_e32 v37, v241, v37
	v_mul_f32_e32 v38, v241, v38
	v_mul_f32_e32 v39, v241, v39
	v_mul_f32_e32 v40, v241, v40
	v_mul_f32_e32 v41, v241, v41
	v_mul_f32_e32 v42, v241, v42
	v_mul_f32_e32 v43, v241, v43
	v_mul_f32_e32 v44, v241, v44
	v_mul_f32_e32 v45, v241, v45
	v_mul_f32_e32 v46, v241, v46
	v_mul_f32_e32 v47, v241, v47
	v_mul_f32_e32 v48, v241, v48
	v_mul_f32_e32 v49, v241, v49
	v_mul_f32_e32 v50, v241, v50
	v_mul_f32_e32 v51, v241, v51
	v_mul_f32_e32 v52, v241, v52
	v_mul_f32_e32 v53, v241, v53
	v_mul_f32_e32 v54, v241, v54
	v_mul_f32_e32 v55, v241, v55
	v_mul_f32_e32 v56, v241, v56
	v_mul_f32_e32 v57, v241, v57
	v_mul_f32_e32 v58, v241, v58
	v_mul_f32_e32 v59, v241, v59
	v_mul_f32_e32 v60, v241, v60
	v_mul_f32_e32 v61, v241, v61
	v_mul_f32_e32 v62, v241, v62
	v_mul_f32_e32 v63, v241, v63
	s_mov_b32 s44, 0
.Lma_skipB:
	s_mov_b32 s3, s38
	s_mov_b32 s38, s40
	s_mov_b32 s40, s39
	s_mov_b32 s39, s3
	s_mov_b32 s3, s41
	s_mov_b32 s41, s43
	s_mov_b32 s43, s42
	s_mov_b32 s42, s3
	s_add_i32 s55, s55, 1
	s_cmpk_lt_u32 s55, 0x80
	s_waitcnt vmcnt(5) lgkmcnt(0)
	s_barrier
	s_cbranch_scc1 .Lma_loop
	v_add_u32_e32 v244, s42, v184
	v_add_u32_e32 v245, s42, v183
	v_add_u32_e32 v246, s42, v182
	v_add_u32_e32 v247, s42, v181
	v_sub_f32_e32 v80, v80, v243
	v_sub_f32_e32 v81, v81, v243
	v_exp_f32_e32 v80, v80
	v_exp_f32_e32 v81, v81
	v_add_f32_e32 v192, v192, v80
	v_add_f32_e32 v193, v193, v81
	v_sub_f32_e32 v82, v82, v243
	v_sub_f32_e32 v83, v83, v243
	v_exp_f32_e32 v82, v82
	v_exp_f32_e32 v83, v83
	v_add_f32_e32 v192, v192, v82
	v_add_f32_e32 v193, v193, v83
	v_sub_f32_e32 v84, v84, v243
	v_sub_f32_e32 v85, v85, v243
	v_exp_f32_e32 v84, v84
	v_exp_f32_e32 v85, v85
	v_add_f32_e32 v192, v192, v84
	v_add_f32_e32 v193, v193, v85
	v_sub_f32_e32 v86, v86, v243
	v_sub_f32_e32 v87, v87, v243
	v_exp_f32_e32 v86, v86
	v_exp_f32_e32 v87, v87
	v_add_f32_e32 v192, v192, v86
	v_add_f32_e32 v193, v193, v87
	v_sub_f32_e32 v88, v88, v243
	v_sub_f32_e32 v89, v89, v243
	v_exp_f32_e32 v88, v88
	v_exp_f32_e32 v89, v89
	v_add_f32_e32 v192, v192, v88
	v_add_f32_e32 v193, v193, v89
	v_sub_f32_e32 v90, v90, v243
	v_sub_f32_e32 v91, v91, v243
	v_exp_f32_e32 v90, v90
	v_exp_f32_e32 v91, v91
	v_add_f32_e32 v192, v192, v90
	v_add_f32_e32 v193, v193, v91
	v_sub_f32_e32 v92, v92, v243
	v_sub_f32_e32 v93, v93, v243
	v_exp_f32_e32 v92, v92
	v_exp_f32_e32 v93, v93
	v_add_f32_e32 v192, v192, v92
	v_add_f32_e32 v193, v193, v93
	v_sub_f32_e32 v94, v94, v243
	v_sub_f32_e32 v95, v95, v243
	v_exp_f32_e32 v94, v94
	v_exp_f32_e32 v95, v95
	v_add_f32_e32 v192, v192, v94
	v_add_f32_e32 v193, v193, v95
	v_cvt_pk_bf16_f32 v152, v80, v81
	v_cvt_pk_bf16_f32 v153, v82, v83
	v_cvt_pk_bf16_f32 v154, v84, v85
	v_cvt_pk_bf16_f32 v155, v86, v87
	v_cvt_pk_bf16_f32 v156, v88, v89
	v_cvt_pk_bf16_f32 v157, v90, v91
	v_cvt_pk_bf16_f32 v158, v92, v93
	v_cvt_pk_bf16_f32 v159, v94, v95
	s_nop 1
	ds_read_b128 v[196:199], v244
	ds_read_b128 v[200:203], v244 offset:4096
	ds_read_b128 v[204:207], v244 offset:8192
	ds_read_b128 v[208:211], v244 offset:12288
	ds_read_b128 v[212:215], v245
	ds_read_b128 v[216:219], v245 offset:4096
	ds_read_b128 v[220:223], v245 offset:8192
	ds_read_b128 v[224:227], v245 offset:12288
	ds_read_b128 v[228:231], v246
	s_waitcnt lgkmcnt(7)
	v_mfma_f32_32x32x16_bf16 v[48:63], v[196:199], v[144:147], v[48:63]
	v_mfma_f32_32x32x16_bf16 v[32:47], v[200:203], v[144:147], v[32:47]
	ds_read_b128 v[236:239], v246 offset:4096
	s_waitcnt lgkmcnt(6)
	v_mfma_f32_32x32x16_bf16 v[16:31], v[204:207], v[144:147], v[16:31]
	ds_read_b128 v[196:199], v246 offset:8192
	v_mfma_f32_32x32x16_bf16 v[0:15], v[208:211], v[144:147], v[0:15]
	ds_read_b128 v[200:203], v246 offset:12288
	s_waitcnt lgkmcnt(6)
	v_mfma_f32_32x32x16_bf16 v[48:63], v[212:215], v[148:151], v[48:63]
	ds_read_b128 v[204:207], v247
	v_mfma_f32_32x32x16_bf16 v[32:47], v[216:219], v[148:151], v[32:47]
	ds_read_b128 v[208:211], v247 offset:4096
	s_waitcnt lgkmcnt(6)
	v_mfma_f32_32x32x16_bf16 v[16:31], v[220:223], v[148:151], v[16:31]
	ds_read_b128 v[212:215], v247 offset:8192
	v_mfma_f32_32x32x16_bf16 v[0:15], v[224:227], v[148:151], v[0:15]
	ds_read_b128 v[216:219], v247 offset:12288
	s_waitcnt lgkmcnt(6)
	v_mfma_f32_32x32x16_bf16 v[48:63], v[228:231], v[152:155], v[48:63]
	v_mfma_f32_32x32x16_bf16 v[32:47], v[236:239], v[152:155], v[32:47]
	s_waitcnt lgkmcnt(4)
	v_mfma_f32_32x32x16_bf16 v[16:31], v[196:199], v[152:155], v[16:31]
	v_mfma_f32_32x32x16_bf16 v[0:15], v[200:203], v[152:155], v[0:15]
	s_waitcnt lgkmcnt(2)
	v_mfma_f32_32x32x16_bf16 v[48:63], v[204:207], v[156:159], v[48:63]
	v_mfma_f32_32x32x16_bf16 v[32:47], v[208:211], v[156:159], v[32:47]
	s_waitcnt lgkmcnt(0)
	v_mfma_f32_32x32x16_bf16 v[16:31], v[212:215], v[156:159], v[16:31]
	v_mfma_f32_32x32x16_bf16 v[0:15], v[216:219], v[156:159], v[0:15]
	s_waitcnt vmcnt(0) lgkmcnt(0)
	s_barrier
	v_add_f32_e32 v185, v192, v193
	v_lshlrev_b32_e32 v232, 3, v179
	s_mov_b32 m0, s45
	s_lshl_b32 s36, s54, 1
	s_add_i32 s17, s17, s52
	s_cmpk_gt_i32 s17, 0x1ff
	s_branch .Lma_epi
.Lma_rareA:
	v_max_f32_e32 v240, 0, v242
	v_exp_f32_e64 v241, -v240
	v_add_f32_e32 v243, v243, v240
	s_mov_b32 s44, 1
	v_mul_f32_e32 v192, v192, v241
	v_mul_f32_e32 v193, v193, v241
	s_branch .Lma_backA
